# attention loops: V-fragment LDS reads issued 3 MFMA gaps ahead (was 2), lgkmcnt waits rederived
# speedup vs baseline: 1.0034x; 1.0007x over previous
.LBB0_512:
	s_waitcnt lgkmcnt(2)
	v_mfma_f32_32x32x16_bf16 v[50:65], v[162:165], v[122:125], v[50:65]
	ds_read_b64_tr_b16 v[126:127], v222 offset:1024
	ds_read_b64_tr_b16 v[128:129], v222 offset:3072
	ds_read_b64_tr_b16 v[122:123], v222 offset:1536
	ds_read_b64_tr_b16 v[124:125], v222 offset:3584
	v_mfma_f32_16x16x32_bf16 v[240:243], v[114:117], v[236:239], v[240:243]
	v_cndmask_b32_e64 v166, v221, v223, s[4:5]
	v_exp_f32_e32 v98, v98
	v_exp_f32_e32 v99, v99
	s_waitcnt lgkmcnt(4)
	v_mfma_f32_32x32x16_bf16 v[66:81], v[162:165], v[118:121], v[66:81]
	ds_read_b64_tr_b16 v[118:119], v222 offset:4096
	ds_read_b64_tr_b16 v[120:121], v222 offset:6144
	v_exp_f32_e32 v100, v100
	v_exp_f32_e32 v101, v101
	s_waitcnt lgkmcnt(4)
	v_mfma_f32_32x32x16_bf16 v[2:17], v[162:165], v[126:129], v[2:17]
	ds_read_b64_tr_b16 v[126:127], v222 offset:4608
	ds_read_b64_tr_b16 v[128:129], v222 offset:6656
	v_exp_f32_e32 v102, v102
	v_exp_f32_e32 v103, v103
	s_waitcnt lgkmcnt(4)
	v_mfma_f32_32x32x16_bf16 v[18:33], v[162:165], v[122:125], v[18:33]
	ds_read_b64_tr_b16 v[122:123], v222 offset:5120
	ds_read_b64_tr_b16 v[124:125], v222 offset:7168
	v_exp_f32_e32 v104, v104
	v_exp_f32_e32 v105, v105
	s_waitcnt lgkmcnt(4)
	v_mfma_f32_32x32x16_bf16 v[50:65], v[134:137], v[118:121], v[50:65]
	ds_read_b64_tr_b16 v[118:119], v222 offset:5632
	ds_read_b64_tr_b16 v[120:121], v222 offset:7680
	v_exp_f32_e32 v106, v106
	v_exp_f32_e32 v107, v107
	s_waitcnt lgkmcnt(4)
	v_mfma_f32_32x32x16_bf16 v[66:81], v[134:137], v[126:129], v[66:81]
	ds_read_b64_tr_b16 v[126:127], v222 offset:8192
	ds_read_b64_tr_b16 v[128:129], v222 offset:10240
	v_exp_f32_e32 v108, v108
	v_exp_f32_e32 v109, v109
	s_waitcnt lgkmcnt(4)
	v_mfma_f32_32x32x16_bf16 v[2:17], v[134:137], v[122:125], v[2:17]
	ds_read_b64_tr_b16 v[122:123], v222 offset:8704
	ds_read_b64_tr_b16 v[124:125], v222 offset:10752
	v_exp_f32_e32 v110, v110
	v_exp_f32_e32 v111, v111
	s_waitcnt lgkmcnt(4)
	v_mfma_f32_32x32x16_bf16 v[18:33], v[134:137], v[118:121], v[18:33]
	ds_read_b64_tr_b16 v[118:119], v222 offset:9216
	ds_read_b64_tr_b16 v[120:121], v222 offset:11264
	v_exp_f32_e32 v112, v112
	v_exp_f32_e32 v113, v113
	s_waitcnt lgkmcnt(4)
	v_mfma_f32_32x32x16_bf16 v[50:65], v[130:133], v[126:129], v[50:65]
	ds_read_b64_tr_b16 v[126:127], v222 offset:9728
	ds_read_b64_tr_b16 v[128:129], v222 offset:11776
	v_exp_f32_e32 v82, v82
	v_exp_f32_e32 v83, v83
	s_waitcnt lgkmcnt(4)
	v_mfma_f32_32x32x16_bf16 v[66:81], v[130:133], v[122:125], v[66:81]
	ds_read_b64_tr_b16 v[122:123], v222 offset:12288
	ds_read_b64_tr_b16 v[124:125], v222 offset:14336
	v_exp_f32_e32 v84, v84
	v_exp_f32_e32 v85, v85
	s_waitcnt lgkmcnt(4)
	v_mfma_f32_32x32x16_bf16 v[2:17], v[130:133], v[118:121], v[2:17]
	ds_read_b64_tr_b16 v[118:119], v222 offset:12800
	ds_read_b64_tr_b16 v[120:121], v222 offset:14848
	v_exp_f32_e32 v86, v86
	v_exp_f32_e32 v87, v87
	s_waitcnt lgkmcnt(4)
	v_mfma_f32_32x32x16_bf16 v[18:33], v[130:133], v[126:129], v[18:33]
	ds_read_b64_tr_b16 v[126:127], v222 offset:13312
	ds_read_b64_tr_b16 v[128:129], v222 offset:15360
	v_exp_f32_e32 v88, v88
	v_exp_f32_e32 v89, v89
	s_waitcnt lgkmcnt(4)
	v_mfma_f32_32x32x16_bf16 v[50:65], v[114:117], v[122:125], v[50:65]
	ds_read_b64_tr_b16 v[122:123], v222 offset:13824
	ds_read_b64_tr_b16 v[124:125], v222 offset:15872
	v_exp_f32_e32 v90, v90
	v_exp_f32_e32 v91, v91
	s_waitcnt lgkmcnt(4)
	v_mfma_f32_32x32x16_bf16 v[66:81], v[114:117], v[118:121], v[66:81]
	v_exp_f32_e32 v92, v92
	v_exp_f32_e32 v93, v93
	s_waitcnt lgkmcnt(2)
	v_mfma_f32_32x32x16_bf16 v[2:17], v[114:117], v[126:129], v[2:17]
	v_exp_f32_e32 v94, v94
	v_exp_f32_e32 v95, v95
	s_waitcnt lgkmcnt(0)
	v_mfma_f32_32x32x16_bf16 v[18:33], v[114:117], v[122:125], v[18:33]
	v_exp_f32_e32 v96, v96
	v_exp_f32_e32 v97, v97
	s_add_i32 s4, s9, 1
	s_cmp_lg_u32 s9, 4
	s_cselect_b32 s14, s4, 0
	s_add_i32 s67, s67, 2
	s_addk_i32 s66, 0x80
	s_add_u32 s40, s40, 0x8000
	s_waitcnt vmcnt(0) lgkmcnt(0)
	s_barrier
	s_addc_u32 s41, s41, 0
	s_add_u32 s46, s46, 0x4000
	v_add_u32_e32 v218, 0x200, v218
	s_addc_u32 s47, s47, 0
	s_and_b64 vcc, exec, s[50:51]
	s_cbranch_vccnz .LBB0_525

.LBB0_519:
	s_waitcnt lgkmcnt(2)
	v_mfma_f32_32x32x16_bf16 v[50:65], v[162:165], v[86:89], v[50:65]
	ds_read_b64_tr_b16 v[94:95], v167 offset:1024
	ds_read_b64_tr_b16 v[96:97], v167 offset:3072
	ds_read_b64_tr_b16 v[86:87], v167 offset:1536
	ds_read_b64_tr_b16 v[88:89], v167 offset:3584
	v_mfma_f32_16x16x32_bf16 v[240:243], v[82:85], v[236:239], v[240:243]
	v_exp_f32_e32 v130, v130
	v_exp_f32_e32 v131, v131
	v_cndmask_b32_e64 v221, v166, v168, s[4:5]
	s_waitcnt lgkmcnt(4)
	v_mfma_f32_32x32x16_bf16 v[66:81], v[162:165], v[90:93], v[66:81]
	ds_read_b64_tr_b16 v[90:91], v167 offset:4096
	ds_read_b64_tr_b16 v[92:93], v167 offset:6144
	v_exp_f32_e32 v132, v132
	v_exp_f32_e32 v133, v133
	s_waitcnt lgkmcnt(4)
	v_mfma_f32_32x32x16_bf16 v[2:17], v[162:165], v[94:97], v[2:17]
	ds_read_b64_tr_b16 v[94:95], v167 offset:4608
	ds_read_b64_tr_b16 v[96:97], v167 offset:6656
	v_exp_f32_e32 v134, v134
	v_exp_f32_e32 v135, v135
	s_waitcnt lgkmcnt(4)
	v_mfma_f32_32x32x16_bf16 v[18:33], v[162:165], v[86:89], v[18:33]
	ds_read_b64_tr_b16 v[86:87], v167 offset:5120
	ds_read_b64_tr_b16 v[88:89], v167 offset:7168
	v_exp_f32_e32 v136, v136
	v_exp_f32_e32 v137, v137
	s_waitcnt lgkmcnt(4)
	v_mfma_f32_32x32x16_bf16 v[50:65], v[102:105], v[90:93], v[50:65]
	ds_read_b64_tr_b16 v[90:91], v167 offset:5632
	ds_read_b64_tr_b16 v[92:93], v167 offset:7680
	v_exp_f32_e32 v138, v138
	v_exp_f32_e32 v139, v139
	s_waitcnt lgkmcnt(4)
	v_mfma_f32_32x32x16_bf16 v[66:81], v[102:105], v[94:97], v[66:81]
	ds_read_b64_tr_b16 v[94:95], v167 offset:8192
	ds_read_b64_tr_b16 v[96:97], v167 offset:10240
	v_exp_f32_e32 v140, v140
	v_exp_f32_e32 v141, v141
	s_waitcnt lgkmcnt(4)
	v_mfma_f32_32x32x16_bf16 v[2:17], v[102:105], v[86:89], v[2:17]
	ds_read_b64_tr_b16 v[86:87], v167 offset:8704
	ds_read_b64_tr_b16 v[88:89], v167 offset:10752
	v_exp_f32_e32 v142, v142
	v_exp_f32_e32 v143, v143
	s_waitcnt lgkmcnt(4)
	v_mfma_f32_32x32x16_bf16 v[18:33], v[102:105], v[90:93], v[18:33]
	ds_read_b64_tr_b16 v[90:91], v167 offset:9216
	ds_read_b64_tr_b16 v[92:93], v167 offset:11264
	v_exp_f32_e32 v144, v144
	v_exp_f32_e32 v145, v145
	s_waitcnt lgkmcnt(4)
	v_mfma_f32_32x32x16_bf16 v[50:65], v[98:101], v[94:97], v[50:65]
	ds_read_b64_tr_b16 v[94:95], v167 offset:9728
	ds_read_b64_tr_b16 v[96:97], v167 offset:11776
	v_exp_f32_e32 v114, v114
	v_exp_f32_e32 v115, v115
	s_waitcnt lgkmcnt(4)
	v_mfma_f32_32x32x16_bf16 v[66:81], v[98:101], v[86:89], v[66:81]
	ds_read_b64_tr_b16 v[86:87], v167 offset:12288
	ds_read_b64_tr_b16 v[88:89], v167 offset:14336
	v_exp_f32_e32 v116, v116
	v_exp_f32_e32 v117, v117
	s_waitcnt lgkmcnt(4)
	v_mfma_f32_32x32x16_bf16 v[2:17], v[98:101], v[90:93], v[2:17]
	ds_read_b64_tr_b16 v[90:91], v167 offset:12800
	ds_read_b64_tr_b16 v[92:93], v167 offset:14848
	v_exp_f32_e32 v118, v118
	v_exp_f32_e32 v119, v119
	s_waitcnt lgkmcnt(4)
	v_mfma_f32_32x32x16_bf16 v[18:33], v[98:101], v[94:97], v[18:33]
	ds_read_b64_tr_b16 v[94:95], v167 offset:13312
	ds_read_b64_tr_b16 v[96:97], v167 offset:15360
	v_exp_f32_e32 v120, v120
	v_exp_f32_e32 v121, v121
	s_waitcnt lgkmcnt(4)
	v_mfma_f32_32x32x16_bf16 v[50:65], v[82:85], v[86:89], v[50:65]
	ds_read_b64_tr_b16 v[86:87], v167 offset:13824
	ds_read_b64_tr_b16 v[88:89], v167 offset:15872
	v_exp_f32_e32 v122, v122
	v_exp_f32_e32 v123, v123
	s_waitcnt lgkmcnt(4)
	v_mfma_f32_32x32x16_bf16 v[66:81], v[82:85], v[90:93], v[66:81]
	v_exp_f32_e32 v124, v124
	v_exp_f32_e32 v125, v125
	s_waitcnt lgkmcnt(2)
	v_mfma_f32_32x32x16_bf16 v[2:17], v[82:85], v[94:97], v[2:17]
	v_exp_f32_e32 v126, v126
	v_exp_f32_e32 v127, v127
	s_waitcnt lgkmcnt(0)
	v_mfma_f32_32x32x16_bf16 v[18:33], v[82:85], v[86:89], v[18:33]
	v_exp_f32_e32 v128, v128
	v_exp_f32_e32 v129, v129
	s_add_i32 s4, s14, -4
	s_add_i32 s9, s14, 1
	s_cmp_gt_i32 s14, 3
	s_cselect_b32 s4, s4, s9
	v_lshl_add_u32 v86, s4, 13, v205
	s_add_i32 s4, s66, 0xffffff42
	s_cmpk_lt_i32 s4, 0xff42
	s_cselect_b64 vcc, -1, 0
	s_cmpk_gt_i32 s4, 0x9e
	ds_read_b128 v[82:85], v86
	ds_read_b128 v[166:169], v86 offset:512
	s_cselect_b64 s[4:5], -1, 0
	v_cndmask_b32_e64 v86, 0, v207, s[4:5]
	v_cndmask_b32_e32 v223, v86, v206, vcc
	v_cmp_eq_f32_e32 vcc, v223, v221
	v_cmp_neq_f32_e64 s[4:5], v223, v221
	s_cbranch_vccnz .LBB0_521
	v_sub_f32_e32 v34, v223, v217
	v_mov_b32_e32 v35, v34
	v_mov_b32_e32 v36, v34
	v_mov_b32_e32 v37, v34
	v_mov_b32_e32 v38, v34
	v_mov_b32_e32 v39, v34
	v_mov_b32_e32 v40, v34
	v_mov_b32_e32 v41, v34
	v_mov_b32_e32 v42, v34
	v_mov_b32_e32 v43, v34
	v_mov_b32_e32 v44, v34
	v_mov_b32_e32 v45, v34
	v_mov_b32_e32 v46, v34
	v_mov_b32_e32 v47, v34
	v_mov_b32_e32 v48, v34
	v_mov_b32_e32 v49, v34

.LBB0_590:
	s_waitcnt lgkmcnt(2)
	v_mfma_f32_32x32x16_bf16 v[16:31], v[128:131], v[48:51], v[16:31]
	ds_read_b64_tr_b16 v[56:57], v15 offset:2048
	ds_read_b64_tr_b16 v[58:59], v15 offset:3072
	ds_read_b64_tr_b16 v[48:49], v15 offset:2560
	ds_read_b64_tr_b16 v[50:51], v15 offset:3584
	v_mfma_f32_16x16x32_bf16 v[144:147], v[2:5], v[140:143], v[144:147]
	v_exp_f32_e32 v96, v96
	v_exp_f32_e32 v97, v97
	v_exp_f32_e32 v98, v98
	v_exp_f32_e32 v99, v99
	s_waitcnt lgkmcnt(4)
	v_mfma_f32_32x32x16_bf16 v[32:47], v[128:131], v[52:55], v[32:47]
	ds_read_b64_tr_b16 v[52:53], v15 offset:4096
	ds_read_b64_tr_b16 v[54:55], v15 offset:5120
	v_exp_f32_e32 v100, v100
	v_exp_f32_e32 v101, v101
	v_exp_f32_e32 v102, v102
	v_exp_f32_e32 v103, v103
	s_waitcnt lgkmcnt(4)
	v_mfma_f32_32x32x16_bf16 v[16:31], v[10:13], v[56:59], v[16:31]
	ds_read_b64_tr_b16 v[56:57], v15 offset:4608
	ds_read_b64_tr_b16 v[58:59], v15 offset:5632
	v_exp_f32_e32 v104, v104
	v_exp_f32_e32 v105, v105
	v_exp_f32_e32 v106, v106
	v_exp_f32_e32 v107, v107
	s_waitcnt lgkmcnt(4)
	v_mfma_f32_32x32x16_bf16 v[32:47], v[10:13], v[48:51], v[32:47]
	ds_read_b64_tr_b16 v[10:11], v15 offset:6144
	ds_read_b64_tr_b16 v[12:13], v15 offset:7168
	v_exp_f32_e32 v108, v108
	v_exp_f32_e32 v109, v109
	v_exp_f32_e32 v110, v110
	v_exp_f32_e32 v111, v111
	s_waitcnt lgkmcnt(4)
	v_mfma_f32_32x32x16_bf16 v[16:31], v[6:9], v[52:55], v[16:31]
	ds_read_b64_tr_b16 v[48:49], v15 offset:6656
	ds_read_b64_tr_b16 v[50:51], v15 offset:7680
	v_exp_f32_e32 v80, v80
	v_exp_f32_e32 v81, v81
	v_exp_f32_e32 v82, v82
	v_exp_f32_e32 v83, v83
	s_waitcnt lgkmcnt(4)
	v_mfma_f32_32x32x16_bf16 v[32:47], v[6:9], v[56:59], v[32:47]
	v_exp_f32_e32 v84, v84
	v_exp_f32_e32 v85, v85
	v_exp_f32_e32 v86, v86
	v_exp_f32_e32 v87, v87
	s_waitcnt lgkmcnt(2)
	v_mfma_f32_32x32x16_bf16 v[16:31], v[2:5], v[10:13], v[16:31]
	v_exp_f32_e32 v88, v88
	v_exp_f32_e32 v89, v89
	v_exp_f32_e32 v90, v90
	v_exp_f32_e32 v91, v91
	s_waitcnt lgkmcnt(0)
	v_mfma_f32_32x32x16_bf16 v[32:47], v[2:5], v[48:51], v[32:47]
	v_exp_f32_e32 v92, v92
	v_exp_f32_e32 v93, v93
	v_exp_f32_e32 v94, v94
	v_exp_f32_e32 v95, v95
	s_add_i32 s12, s8, -4
	s_add_i32 s13, s8, 1
	s_cmp_gt_i32 s8, 3
	s_cselect_b32 s12, s12, s13
	v_lshl_add_u32 v6, s12, 13, v135
	ds_read_b128 v[2:5], v6
	ds_read_b128 v[6:9], v6 offset:512
	s_cmp_lg_u32 s8, 4
	s_cselect_b32 s54, s13, 0
	v_lshl_add_u32 v15, s54, 13, v135
	v_lshl_add_u32 v128, s8, 14, v1
	s_waitcnt lgkmcnt(1)
	v_mfma_f32_32x32x16_bf16 v[64:79], v[2:5], v[124:127], 0
	ds_read_b128 v[10:13], v15 offset:2048
	v_cvt_pk_bf16_f32 v2, v96, v97
	v_cvt_pk_bf16_f32 v3, v98, v99
	s_nop 0
	ds_read_b128 v[96:99], v15 offset:2560
	v_cvt_pk_bf16_f32 v4, v100, v101
	s_waitcnt lgkmcnt(2)
	v_mfma_f32_32x32x16_bf16 v[48:63], v[6:9], v[124:127], 0
	v_cvt_pk_bf16_f32 v5, v102, v103
	s_waitcnt lgkmcnt(1)
	v_mfma_f32_32x32x16_bf16 v[64:79], v[10:13], v[120:123], v[64:79]
	ds_read_b128 v[6:9], v15 offset:4096
	v_mfma_f32_16x16x32_bf16 v[144:147], v[2:5], v[140:143], v[144:147]
	v_cvt_pk_bf16_f32 v10, v104, v105
	v_cvt_pk_bf16_f32 v11, v106, v107
	s_waitcnt lgkmcnt(1)
	v_mfma_f32_32x32x16_bf16 v[48:63], v[96:99], v[120:123], v[48:63]
	ds_read_b128 v[100:103], v15 offset:4608
	v_cvt_pk_bf16_f32 v12, v108, v109
	v_cvt_pk_bf16_f32 v13, v110, v111
	s_waitcnt lgkmcnt(1)
	v_mfma_f32_32x32x16_bf16 v[64:79], v[6:9], v[116:119], v[64:79]
	ds_read_b128 v[96:99], v15 offset:6144
	v_mfma_f32_16x16x32_bf16 v[144:147], v[10:13], v[140:143], v[144:147]
	v_cvt_pk_bf16_f32 v6, v80, v81
	v_cvt_pk_bf16_f32 v7, v82, v83
	s_waitcnt lgkmcnt(1)
	v_mfma_f32_32x32x16_bf16 v[48:63], v[100:103], v[116:119], v[48:63]
	ds_read_b128 v[80:83], v15 offset:6656
	v_cvt_pk_bf16_f32 v8, v84, v85
	v_cvt_pk_bf16_f32 v9, v86, v87
	s_waitcnt lgkmcnt(1)
	v_mfma_f32_32x32x16_bf16 v[64:79], v[96:99], v[112:115], v[64:79]
	v_mfma_f32_16x16x32_bf16 v[144:147], v[6:9], v[140:143], v[144:147]
	v_cvt_pk_bf16_f32 v84, v88, v89
	v_cvt_pk_bf16_f32 v85, v90, v91
	ds_read_b64_tr_b16 v[88:89], v128
	ds_read_b64_tr_b16 v[90:91], v128 offset:1024
	s_waitcnt lgkmcnt(2)
	v_mfma_f32_32x32x16_bf16 v[48:63], v[80:83], v[112:115], v[48:63]
	v_cvt_pk_bf16_f32 v86, v92, v93
	v_cvt_pk_bf16_f32 v87, v94, v95
	ds_read_b64_tr_b16 v[80:81], v128 offset:512
	ds_read_b64_tr_b16 v[82:83], v128 offset:1536
	s_waitcnt lgkmcnt(2)
	v_mfma_f32_32x32x16_bf16 v[16:31], v[2:5], v[88:91], v[16:31]
	ds_read_b64_tr_b16 v[92:93], v128 offset:2048
	ds_read_b64_tr_b16 v[94:95], v128 offset:3072
	ds_read_b64_tr_b16 v[88:89], v128 offset:2560
	ds_read_b64_tr_b16 v[90:91], v128 offset:3584
	v_mfma_f32_16x16x32_bf16 v[144:147], v[84:87], v[140:143], v[144:147]
	v_exp_f32_e32 v64, v64
	v_exp_f32_e32 v65, v65
	v_exp_f32_e32 v66, v66
	v_exp_f32_e32 v67, v67
	s_waitcnt lgkmcnt(4)
	v_mfma_f32_32x32x16_bf16 v[32:47], v[2:5], v[80:83], v[32:47]
	ds_read_b64_tr_b16 v[2:3], v128 offset:4096
	ds_read_b64_tr_b16 v[4:5], v128 offset:5120
	v_exp_f32_e32 v68, v68
	v_exp_f32_e32 v69, v69
	v_exp_f32_e32 v70, v70
	v_exp_f32_e32 v71, v71
	s_waitcnt lgkmcnt(4)
	v_mfma_f32_32x32x16_bf16 v[16:31], v[10:13], v[92:95], v[16:31]
	ds_read_b64_tr_b16 v[80:81], v128 offset:4608
	ds_read_b64_tr_b16 v[82:83], v128 offset:5632
	v_exp_f32_e32 v72, v72
	v_exp_f32_e32 v73, v73
	v_exp_f32_e32 v74, v74
	v_exp_f32_e32 v75, v75
	s_waitcnt lgkmcnt(4)
	v_mfma_f32_32x32x16_bf16 v[32:47], v[10:13], v[88:91], v[32:47]
	ds_read_b64_tr_b16 v[10:11], v128 offset:6144
	ds_read_b64_tr_b16 v[12:13], v128 offset:7168
	v_exp_f32_e32 v76, v76
	v_exp_f32_e32 v77, v77
	v_exp_f32_e32 v78, v78
	v_exp_f32_e32 v79, v79
	s_waitcnt lgkmcnt(4)
	v_mfma_f32_32x32x16_bf16 v[16:31], v[6:9], v[2:5], v[16:31]
	ds_read_b64_tr_b16 v[2:3], v128 offset:6656
	ds_read_b64_tr_b16 v[4:5], v128 offset:7680
	v_exp_f32_e32 v48, v48
	v_exp_f32_e32 v49, v49
	v_exp_f32_e32 v50, v50
	v_exp_f32_e32 v51, v51
	s_waitcnt lgkmcnt(4)
	v_mfma_f32_32x32x16_bf16 v[32:47], v[6:9], v[80:83], v[32:47]
	v_exp_f32_e32 v52, v52
	v_exp_f32_e32 v53, v53
	v_exp_f32_e32 v54, v54
	v_exp_f32_e32 v55, v55
	s_waitcnt lgkmcnt(2)
	v_mfma_f32_32x32x16_bf16 v[16:31], v[84:87], v[10:13], v[16:31]
	v_exp_f32_e32 v56, v56
	v_exp_f32_e32 v57, v57
	v_exp_f32_e32 v58, v58
	v_exp_f32_e32 v59, v59
	s_waitcnt lgkmcnt(0)
	v_mfma_f32_32x32x16_bf16 v[32:47], v[84:87], v[2:5], v[32:47]
	v_exp_f32_e32 v60, v60
	v_exp_f32_e32 v61, v61
	v_exp_f32_e32 v62, v62
	v_exp_f32_e32 v63, v63
	s_add_i32 s8, s54, 1
	s_cmp_lg_u32 s54, 4
	s_cselect_b32 s8, s8, 0
	s_add_u32 s6, s6, 0x4000
	s_addc_u32 s7, s7, 0
	s_add_u32 s40, s40, 0x4000
	s_waitcnt vmcnt(0) lgkmcnt(0)
	s_barrier
	s_addc_u32 s41, s41, 0
	s_add_i32 s49, s49, 2
	s_cmp_lt_u32 s51, s50
	s_cbranch_scc0 .LBB0_596
